# speedup vs baseline: 1.0205x; 1.0045x over previous
; __device__ __forceinline__ void convert_w(const float* __restrict__ src, int K, int Ns, u16* __restrict__ dst, int Nd, int mapmode,
;                           char* shmc, int tid, int bfirst, int bstride) {
;   u16* lds = (u16*)shmc;
;   const int ntn = Nd >> 6, ntk = K >> 6, ntiles = ntn * ntk;
;   for (int tile = bfirst; tile < ntiles; tile += bstride) {
;     const int tn = tile % ntn, tk = tile / ntn, n0 = tn * 64, k0 = tk * 64;
.LBB0_114:
	s_lshr_b32 s20, s28, 6
	s_mul_i32 s29, s27, s20
	s_cmp_ge_i32 s24, s29
	s_cbranch_scc1 .LBB0_83
	v_mov_b64_e32 v[8:9], s[62:63]
	flat_load_dwordx2 v[8:9], v[8:9] offset:136
	v_cvt_f32_u32_e32 v10, s27
	s_lshl_b32 s21, s27, 6
	s_sub_i32 s20, 0, s27
	s_sub_i32 s37, 0, s21
	v_rcp_iflag_f32_e32 v10, v10
	s_lshl_b32 s30, s23, 6
	s_mov_b32 s31, s25
	s_mov_b32 s49, s24
	v_mul_f32_e32 v10, 0x4f7ffffe, v10
	v_cvt_u32_f32_e32 v10, v10
	s_waitcnt vmcnt(0) lgkmcnt(0)
	v_lshl_add_u64 v[8:9], v[8:9], 0, s[8:9]
	v_readfirstlane_b32 s21, v10
	s_mul_i32 s20, s20, s21
	s_mul_hi_u32 s20, s21, s20
	s_add_i32 s48, s21, s20
	s_mov_b32 s100, 0
	s_branch .LBB0_117

; __device__ __forceinline__ void stg16(void* p, uint4 a) { const u32x4 v = {a.x, a.y, a.z, a.w}; *(__attribute__((address_space(1))) u32x4*)(p) = v; }
; __device__ __forceinline__ float ldg4f(const void* p) { return *(const __attribute__((address_space(1))) float*)(p); }
; __device__ __forceinline__ void convert_w(const float* __restrict__ src, int K, int Ns, u16* __restrict__ dst, int Nd, int mapmode,
;                           char* shmc, int tid, int bfirst, int bstride) {
;     ...
; #pragma unroll
;     for (int j = 0; j < 8; ++j) {
;       const int e = j * 512 + tid, kk = e >> 6, nn = e & 63;
;       const int sc = wmap(n0 + nn, mapmode);
;       float v = 0.f;
;       if (sc >= 0) v = ldg4f(src + (long)(k0 + kk) * Ns + sc);
;       lds[nn * 66 + kk] = f2bf(v);
;     }
;     __syncthreads();
;     {
;       const int n = tid >> 3, kg = (tid & 7) * 8;
;       const unsigned* s32 = (const unsigned*)(lds + n * 66 + kg);
;       uint4 o; o.x = s32[0]; o.y = s32[1]; o.z = s32[2]; o.w = s32[3];
;       stg16(dst + (long)(n0 + n) * K + k0 + kg, o);
;     }
;     __syncthreads();
.Lcv_skip:
	s_mov_b64 exec, s[20:21]
	s_cmp_eq_u32 s100, 0
	s_cbranch_scc1 .Lcv_nostore
	s_waitcnt lgkmcnt(0)
	s_barrier
	ds_read2_b32 v[32:33], v14 offset1:1
	ds_read2_b32 v[34:35], v14 offset0:2 offset1:3
	s_waitcnt lgkmcnt(0)
	global_store_dwordx4 v[38:39], v[32:35], off
	s_barrier
.Lcv_nostore:
	v_add_u32_e32 v10, s59, v13
	v_ashrrev_i32_e32 v31, 31, v10
	v_mad_u64_u32 v[10:11], s[20:21], v10, s28, 0
	v_mov_b32_e32 v36, v11
	v_mad_u64_u32 v[36:37], s[20:21], v31, s28, v[36:37]
	v_mov_b32_e32 v11, v36
	v_lshl_add_u64 v[10:11], v[10:11], 1, v[8:9]
	s_ashr_i32 s9, s8, 31
	v_lshl_add_u64 v[10:11], s[8:9], 1, v[10:11]
	v_lshl_add_u64 v[38:39], v[10:11], 0, v[212:213]
	s_waitcnt vmcnt(0)
	v_cvt_pk_bf16_f32 v41, v41, s0
	v_cvt_pk_bf16_f32 v42, v42, s0
	v_cvt_pk_bf16_f32 v43, v43, s0
	v_cvt_pk_bf16_f32 v44, v44, s0
	v_cvt_pk_bf16_f32 v45, v45, s0
	v_cvt_pk_bf16_f32 v46, v46, s0
	v_cvt_pk_bf16_f32 v47, v47, s0
	v_cvt_pk_bf16_f32 v48, v48, s0
	ds_write_b16 v16, v41
	ds_write_b16 v18, v42
	ds_write_b16 v20, v43
	ds_write_b16 v22, v44
	ds_write_b16 v24, v45
	ds_write_b16 v26, v46
	ds_write_b16 v28, v47
	ds_write_b16 v30, v48
	s_mov_b32 s100, 1
	s_add_i32 s49, s49, s23
	s_add_i32 s31, s31, s30
	s_cmp_lt_i32 s49, s29
	s_cbranch_scc1 .LBB0_117
	s_waitcnt lgkmcnt(0)
	s_barrier
	ds_read2_b32 v[32:33], v14 offset1:1
	ds_read2_b32 v[34:35], v14 offset0:2 offset1:3
	s_waitcnt lgkmcnt(0)
	global_store_dwordx4 v[38:39], v[32:35], off
	s_barrier
	s_branch .LBB0_83

; __global__ __launch_bounds__(512) void mk(Params p_arg, int ph0, int ph1) {
	.amdhsa_kernel _Z2mk6Paramsii
		.amdhsa_group_segment_fixed_size 272
		.amdhsa_private_segment_fixed_size 0
		.amdhsa_kernarg_size 408
		.amdhsa_user_sgpr_count 2
		.amdhsa_user_sgpr_dispatch_ptr 0
		.amdhsa_user_sgpr_queue_ptr 0
		.amdhsa_user_sgpr_kernarg_segment_ptr 1
		.amdhsa_user_sgpr_dispatch_id 0
		.amdhsa_user_sgpr_kernarg_preload_length 0
		.amdhsa_user_sgpr_kernarg_preload_offset 0
		.amdhsa_user_sgpr_private_segment_size 0
		.amdhsa_uses_dynamic_stack 0
		.amdhsa_enable_private_segment 0
		.amdhsa_system_sgpr_workgroup_id_x 1
		.amdhsa_system_sgpr_workgroup_id_y 0
		.amdhsa_system_sgpr_workgroup_id_z 0
		.amdhsa_system_sgpr_workgroup_info 0
		.amdhsa_system_vgpr_workitem_id 2
		.amdhsa_next_free_vgpr 256
		.amdhsa_next_free_sgpr 102
		.amdhsa_accum_offset 256
		.amdhsa_reserve_vcc 1
		.amdhsa_float_round_mode_32 0
		.amdhsa_float_round_mode_16_64 0
		.amdhsa_float_denorm_mode_32 3
		.amdhsa_float_denorm_mode_16_64 3
		.amdhsa_dx10_clamp 1
		.amdhsa_ieee_mode 1
		.amdhsa_fp16_overflow 0
		.amdhsa_tg_split 0
		.amdhsa_exception_fp_ieee_invalid_op 0
		.amdhsa_exception_fp_denorm_src 0
		.amdhsa_exception_fp_ieee_div_zero 0
		.amdhsa_exception_fp_ieee_overflow 0
		.amdhsa_exception_fp_ieee_underflow 0
		.amdhsa_exception_fp_ieee_inexact 0
		.amdhsa_exception_int_div_zero 0
	.end_amdhsa_kernel
